# grid barrier release counter replicated per XCC (leader adds to 16 replicas, each workgroup polls its own XCC replica)
# baseline (speedup 1.0000x reference)
; __device__ __forceinline__ unsigned xb_ld(unsigned* p)              { return __hip_atomic_load(p, __ATOMIC_RELAXED, __HIP_MEMORY_SCOPE_AGENT); }
; __device__ __forceinline__ unsigned xb_add(unsigned* p, unsigned v) { return __hip_atomic_fetch_add(p, v, __ATOMIC_RELAXED, __HIP_MEMORY_SCOPE_AGENT); }
; #define XB_SPIN(cond, bar) do { unsigned _sp = 0; while (cond) { __builtin_amdgcn_s_sleep(1); \
;     if ((++_sp & 255u) == 0u) { if (xb_ld(&(bar)[XB_TMO])) break; if (_sp > XB_SPIN_CAP) { atomicAdd(&(bar)[XB_TMO], 1u); break; } } } } while (0)
; __device__ __forceinline__ void xcd_barrier(const XcdBarrier& b) {
;     asm volatile("s_waitcnt vmcnt(0)" ::: "memory");
;     __syncthreads();
;     if (threadIdx.x == 0) {
;         unsigned* bar = b.bar;
;         __builtin_amdgcn_s_waitcnt(0);
;         unsigned nloc = b.st[0], nx = b.st[1];
;         if (nloc == 0u) { xcd_barrier_complete(bar, b.x, nloc, nx); b.st[0] = nloc; b.st[1] = nx; }
;         const unsigned old = xb_add(&bar[XB_XSUB(b.x)], 1u);
;         const unsigned gen = old / nloc;
;         if (old + 1u == (gen + 1u) * nloc) {
;             __builtin_amdgcn_fence(__ATOMIC_RELEASE, "agent");
;             asm volatile("s_waitcnt vmcnt(0)" ::: "memory");
;             const unsigned og = xb_add(&bar[XB_TOP], 1u);
;             const unsigned tg = og / nx;
;             if (og + 1u == (tg + 1u) * nx) xb_add(&bar[XB_TOPGEN], 1u);
;             else XB_SPIN(xb_ld(&bar[XB_TOPGEN]) == tg, bar);
;             __builtin_amdgcn_fence(__ATOMIC_ACQUIRE, "agent");
;             xb_add(&bar[XB_XGEN(b.x)], 1u);
;             asm volatile("s_waitcnt vmcnt(0)" ::: "memory");
;         } else {
;             XB_SPIN(xb_ld(&bar[XB_XGEN(b.x)]) == gen, bar);
;             __builtin_amdgcn_fence(__ATOMIC_ACQUIRE, "agent");
;             asm volatile("s_waitcnt vmcnt(0)" ::: "memory");
;         }
.LBB0_133:
	s_cmp_lt_i32 s27, 3
	s_cbranch_scc1 .LBB0_183
	s_waitcnt vmcnt(0) lgkmcnt(0)
	s_barrier
	v_cmp_eq_u32_e32 vcc, 0, v0
	s_and_saveexec_b64 s[0:1], vcc
	s_cbranch_execz .Lgb1_join
	v_mov_b32_e32 v1, s85
	ds_read_b32 v2, v1
	ds_read_b32 v3, v1 offset:4
	s_lshl_b32 s4, s84, 8
	s_add_u32 s4, s22, s4
	s_addc_u32 s5, s23, 0
	v_mov_b32_e32 v4, 0x1000
	v_mov_b32_e32 v5, 1
	global_atomic_add v5, v4, v5, s[4:5] offset:1024 sc0
	s_lshl_b32 s11, s84, 7
	s_addk_i32 s11, 0x3600
	s_waitcnt lgkmcnt(0)
	v_readfirstlane_b32 s6, v2
	v_readfirstlane_b32 s7, v3
	v_mov_b32_e32 v1, s11
	s_nop 3
	s_mul_i32 s14, s6, 2
	s_add_i32 s14, s14, -1
	s_mul_i32 s7, s7, 1
	s_waitcnt vmcnt(0)
	v_readfirstlane_b32 s15, v5
	v_mov_b32_e32 v4, 0x3600
	s_nop 3
	s_cmp_lg_u32 s15, s14
	s_cbranch_scc1 .Lgb1_poll
	buffer_wbl2 sc1
	s_waitcnt vmcnt(0)
	v_mov_b32_e32 v5, 1
	global_atomic_add v4, v5, s[22:23]
	global_atomic_add v4, v5, s[22:23] offset:128
	global_atomic_add v4, v5, s[22:23] offset:256
	global_atomic_add v4, v5, s[22:23] offset:384
	global_atomic_add v4, v5, s[22:23] offset:512
	global_atomic_add v4, v5, s[22:23] offset:640
	global_atomic_add v4, v5, s[22:23] offset:768
	global_atomic_add v4, v5, s[22:23] offset:896
	global_atomic_add v4, v5, s[22:23] offset:1024
	global_atomic_add v4, v5, s[22:23] offset:1152
	global_atomic_add v4, v5, s[22:23] offset:1280
	global_atomic_add v4, v5, s[22:23] offset:1408
	global_atomic_add v4, v5, s[22:23] offset:1536
	global_atomic_add v4, v5, s[22:23] offset:1664
	global_atomic_add v4, v5, s[22:23] offset:1792
	global_atomic_add v4, v5, s[22:23] offset:1920

; __device__ __forceinline__ unsigned xb_ld(unsigned* p)              { return __hip_atomic_load(p, __ATOMIC_RELAXED, __HIP_MEMORY_SCOPE_AGENT); }
; __device__ __forceinline__ unsigned xb_add(unsigned* p, unsigned v) { return __hip_atomic_fetch_add(p, v, __ATOMIC_RELAXED, __HIP_MEMORY_SCOPE_AGENT); }
; #define XB_SPIN(cond, bar) do { unsigned _sp = 0; while (cond) { __builtin_amdgcn_s_sleep(1); \
;     if ((++_sp & 255u) == 0u) { if (xb_ld(&(bar)[XB_TMO])) break; if (_sp > XB_SPIN_CAP) { atomicAdd(&(bar)[XB_TMO], 1u); break; } } } } while (0)
; __device__ __forceinline__ void xcd_barrier(const XcdBarrier& b) {
;     ...
;             const unsigned og = xb_add(&bar[XB_TOP], 1u);
;             const unsigned tg = og / nx;
;             if (og + 1u == (tg + 1u) * nx) xb_add(&bar[XB_TOPGEN], 1u);
;             else XB_SPIN(xb_ld(&bar[XB_TOPGEN]) == tg, bar);
;             __builtin_amdgcn_fence(__ATOMIC_ACQUIRE, "agent");
.Lgb1_spin:
	global_load_dword v5, v1, s[22:23] sc1
	s_waitcnt vmcnt(0)
	v_readfirstlane_b32 s15, v5
	s_nop 3
	s_cmp_ge_u32 s15, s7
	s_cbranch_scc1 .Lgb1_acq
	s_sleep 1
	s_add_i32 s11, s11, 1
	s_cmp_lt_u32 s11, 0x8000
	s_cbranch_scc1 .Lgb1_spin

; __device__ __forceinline__ unsigned xb_ld(unsigned* p)              { return __hip_atomic_load(p, __ATOMIC_RELAXED, __HIP_MEMORY_SCOPE_AGENT); }
; __device__ __forceinline__ unsigned xb_add(unsigned* p, unsigned v) { return __hip_atomic_fetch_add(p, v, __ATOMIC_RELAXED, __HIP_MEMORY_SCOPE_AGENT); }
; #define XB_SPIN(cond, bar) do { unsigned _sp = 0; while (cond) { __builtin_amdgcn_s_sleep(1); \
;     if ((++_sp & 255u) == 0u) { if (xb_ld(&(bar)[XB_TMO])) break; if (_sp > XB_SPIN_CAP) { atomicAdd(&(bar)[XB_TMO], 1u); break; } } } } while (0)
; __device__ __forceinline__ void xcd_barrier(const XcdBarrier& b) {
;     asm volatile("s_waitcnt vmcnt(0)" ::: "memory");
;     __syncthreads();
;     if (threadIdx.x == 0) {
;         unsigned* bar = b.bar;
;         __builtin_amdgcn_s_waitcnt(0);
;         unsigned nloc = b.st[0], nx = b.st[1];
;         if (nloc == 0u) { xcd_barrier_complete(bar, b.x, nloc, nx); b.st[0] = nloc; b.st[1] = nx; }
;         const unsigned old = xb_add(&bar[XB_XSUB(b.x)], 1u);
;         const unsigned gen = old / nloc;
;         if (old + 1u == (gen + 1u) * nloc) {
;             __builtin_amdgcn_fence(__ATOMIC_RELEASE, "agent");
;             asm volatile("s_waitcnt vmcnt(0)" ::: "memory");
;             const unsigned og = xb_add(&bar[XB_TOP], 1u);
;             const unsigned tg = og / nx;
;             if (og + 1u == (tg + 1u) * nx) xb_add(&bar[XB_TOPGEN], 1u);
;             else XB_SPIN(xb_ld(&bar[XB_TOPGEN]) == tg, bar);
;             __builtin_amdgcn_fence(__ATOMIC_ACQUIRE, "agent");
;             xb_add(&bar[XB_XGEN(b.x)], 1u);
;             asm volatile("s_waitcnt vmcnt(0)" ::: "memory");
;         } else {
;             XB_SPIN(xb_ld(&bar[XB_XGEN(b.x)]) == gen, bar);
;             __builtin_amdgcn_fence(__ATOMIC_ACQUIRE, "agent");
;             asm volatile("s_waitcnt vmcnt(0)" ::: "memory");
;         }
.LBB0_395:
	s_waitcnt vmcnt(0) lgkmcnt(0)
	s_barrier
	v_cmp_eq_u32_e32 vcc, 0, v0
	s_and_saveexec_b64 s[0:1], vcc
	s_cbranch_execz .Lgb2_join
	v_mov_b32_e32 v1, s85
	ds_read_b32 v2, v1
	ds_read_b32 v3, v1 offset:4
	s_lshl_b32 s4, s84, 8
	s_add_u32 s4, s22, s4
	s_addc_u32 s5, s23, 0
	v_mov_b32_e32 v4, 0x1000
	v_mov_b32_e32 v5, 1
	global_atomic_add v5, v4, v5, s[4:5] offset:1024 sc0
	s_lshl_b32 s11, s84, 7
	s_addk_i32 s11, 0x3600
	s_waitcnt lgkmcnt(0)
	v_readfirstlane_b32 s6, v2
	v_readfirstlane_b32 s7, v3
	v_mov_b32_e32 v1, s11
	s_nop 3
	s_mul_i32 s14, s6, 3
	s_add_i32 s14, s14, -1
	s_mul_i32 s7, s7, 2
	s_waitcnt vmcnt(0)
	v_readfirstlane_b32 s15, v5
	v_mov_b32_e32 v4, 0x3600
	s_nop 3
	s_cmp_lg_u32 s15, s14
	s_cbranch_scc1 .Lgb2_poll
	buffer_wbl2 sc1
	s_waitcnt vmcnt(0)
	v_mov_b32_e32 v5, 1
	global_atomic_add v4, v5, s[22:23]
	global_atomic_add v4, v5, s[22:23] offset:128
	global_atomic_add v4, v5, s[22:23] offset:256
	global_atomic_add v4, v5, s[22:23] offset:384
	global_atomic_add v4, v5, s[22:23] offset:512
	global_atomic_add v4, v5, s[22:23] offset:640
	global_atomic_add v4, v5, s[22:23] offset:768
	global_atomic_add v4, v5, s[22:23] offset:896
	global_atomic_add v4, v5, s[22:23] offset:1024
	global_atomic_add v4, v5, s[22:23] offset:1152
	global_atomic_add v4, v5, s[22:23] offset:1280
	global_atomic_add v4, v5, s[22:23] offset:1408
	global_atomic_add v4, v5, s[22:23] offset:1536
	global_atomic_add v4, v5, s[22:23] offset:1664
	global_atomic_add v4, v5, s[22:23] offset:1792
	global_atomic_add v4, v5, s[22:23] offset:1920

; __device__ __forceinline__ unsigned xb_ld(unsigned* p)              { return __hip_atomic_load(p, __ATOMIC_RELAXED, __HIP_MEMORY_SCOPE_AGENT); }
; __device__ __forceinline__ unsigned xb_add(unsigned* p, unsigned v) { return __hip_atomic_fetch_add(p, v, __ATOMIC_RELAXED, __HIP_MEMORY_SCOPE_AGENT); }
; #define XB_SPIN(cond, bar) do { unsigned _sp = 0; while (cond) { __builtin_amdgcn_s_sleep(1); \
;     if ((++_sp & 255u) == 0u) { if (xb_ld(&(bar)[XB_TMO])) break; if (_sp > XB_SPIN_CAP) { atomicAdd(&(bar)[XB_TMO], 1u); break; } } } } while (0)
; __device__ __forceinline__ void xcd_barrier(const XcdBarrier& b) {
;     asm volatile("s_waitcnt vmcnt(0)" ::: "memory");
;     __syncthreads();
;     if (threadIdx.x == 0) {
;         unsigned* bar = b.bar;
;         __builtin_amdgcn_s_waitcnt(0);
;         unsigned nloc = b.st[0], nx = b.st[1];
;         if (nloc == 0u) { xcd_barrier_complete(bar, b.x, nloc, nx); b.st[0] = nloc; b.st[1] = nx; }
;         const unsigned old = xb_add(&bar[XB_XSUB(b.x)], 1u);
;         const unsigned gen = old / nloc;
;         if (old + 1u == (gen + 1u) * nloc) {
;             __builtin_amdgcn_fence(__ATOMIC_RELEASE, "agent");
;             asm volatile("s_waitcnt vmcnt(0)" ::: "memory");
;             const unsigned og = xb_add(&bar[XB_TOP], 1u);
;             const unsigned tg = og / nx;
;             if (og + 1u == (tg + 1u) * nx) xb_add(&bar[XB_TOPGEN], 1u);
;             else XB_SPIN(xb_ld(&bar[XB_TOPGEN]) == tg, bar);
;             __builtin_amdgcn_fence(__ATOMIC_ACQUIRE, "agent");
;             xb_add(&bar[XB_XGEN(b.x)], 1u);
;             asm volatile("s_waitcnt vmcnt(0)" ::: "memory");
;         } else {
;             XB_SPIN(xb_ld(&bar[XB_XGEN(b.x)]) == gen, bar);
;             __builtin_amdgcn_fence(__ATOMIC_ACQUIRE, "agent");
;             asm volatile("s_waitcnt vmcnt(0)" ::: "memory");
;         }
.LBB0_679:
	s_cmp_lt_i32 s27, 5
	s_cbranch_scc1 .LBB0_729
	s_waitcnt vmcnt(0) lgkmcnt(0)
	s_barrier
	v_cmp_eq_u32_e32 vcc, 0, v0
	s_and_saveexec_b64 s[0:1], vcc
	s_cbranch_execz .Lgb3_join
	v_mov_b32_e32 v1, s85
	ds_read_b32 v2, v1
	ds_read_b32 v3, v1 offset:4
	s_lshl_b32 s4, s84, 8
	s_add_u32 s4, s22, s4
	s_addc_u32 s5, s23, 0
	v_mov_b32_e32 v4, 0x1000
	v_mov_b32_e32 v5, 1
	global_atomic_add v5, v4, v5, s[4:5] offset:1024 sc0
	s_lshl_b32 s11, s84, 7
	s_addk_i32 s11, 0x3600
	s_waitcnt lgkmcnt(0)
	v_readfirstlane_b32 s6, v2
	v_readfirstlane_b32 s7, v3
	v_mov_b32_e32 v1, s11
	s_nop 3
	s_mul_i32 s14, s6, 4
	s_add_i32 s14, s14, -1
	s_mul_i32 s7, s7, 3
	s_waitcnt vmcnt(0)
	v_readfirstlane_b32 s15, v5
	v_mov_b32_e32 v4, 0x3600
	s_nop 3
	s_cmp_lg_u32 s15, s14
	s_cbranch_scc1 .Lgb3_poll
	buffer_wbl2 sc1
	s_waitcnt vmcnt(0)
	v_mov_b32_e32 v5, 1
	global_atomic_add v4, v5, s[22:23]
	global_atomic_add v4, v5, s[22:23] offset:128
	global_atomic_add v4, v5, s[22:23] offset:256
	global_atomic_add v4, v5, s[22:23] offset:384
	global_atomic_add v4, v5, s[22:23] offset:512
	global_atomic_add v4, v5, s[22:23] offset:640
	global_atomic_add v4, v5, s[22:23] offset:768
	global_atomic_add v4, v5, s[22:23] offset:896
	global_atomic_add v4, v5, s[22:23] offset:1024
	global_atomic_add v4, v5, s[22:23] offset:1152
	global_atomic_add v4, v5, s[22:23] offset:1280
	global_atomic_add v4, v5, s[22:23] offset:1408
	global_atomic_add v4, v5, s[22:23] offset:1536
	global_atomic_add v4, v5, s[22:23] offset:1664
	global_atomic_add v4, v5, s[22:23] offset:1792
	global_atomic_add v4, v5, s[22:23] offset:1920

; __device__ __forceinline__ unsigned xb_ld(unsigned* p)              { return __hip_atomic_load(p, __ATOMIC_RELAXED, __HIP_MEMORY_SCOPE_AGENT); }
; __device__ __forceinline__ unsigned xb_add(unsigned* p, unsigned v) { return __hip_atomic_fetch_add(p, v, __ATOMIC_RELAXED, __HIP_MEMORY_SCOPE_AGENT); }
; #define XB_SPIN(cond, bar) do { unsigned _sp = 0; while (cond) { __builtin_amdgcn_s_sleep(1); \
;     if ((++_sp & 255u) == 0u) { if (xb_ld(&(bar)[XB_TMO])) break; if (_sp > XB_SPIN_CAP) { atomicAdd(&(bar)[XB_TMO], 1u); break; } } } } while (0)
; __device__ __forceinline__ void xcd_barrier(const XcdBarrier& b) {
;     asm volatile("s_waitcnt vmcnt(0)" ::: "memory");
;     __syncthreads();
;     if (threadIdx.x == 0) {
;         unsigned* bar = b.bar;
;         __builtin_amdgcn_s_waitcnt(0);
;         unsigned nloc = b.st[0], nx = b.st[1];
;         if (nloc == 0u) { xcd_barrier_complete(bar, b.x, nloc, nx); b.st[0] = nloc; b.st[1] = nx; }
;         const unsigned old = xb_add(&bar[XB_XSUB(b.x)], 1u);
;         const unsigned gen = old / nloc;
;         if (old + 1u == (gen + 1u) * nloc) {
;             __builtin_amdgcn_fence(__ATOMIC_RELEASE, "agent");
;             asm volatile("s_waitcnt vmcnt(0)" ::: "memory");
;             const unsigned og = xb_add(&bar[XB_TOP], 1u);
;             const unsigned tg = og / nx;
;             if (og + 1u == (tg + 1u) * nx) xb_add(&bar[XB_TOPGEN], 1u);
;             else XB_SPIN(xb_ld(&bar[XB_TOPGEN]) == tg, bar);
;             __builtin_amdgcn_fence(__ATOMIC_ACQUIRE, "agent");
;             xb_add(&bar[XB_XGEN(b.x)], 1u);
;             asm volatile("s_waitcnt vmcnt(0)" ::: "memory");
;         } else {
;             XB_SPIN(xb_ld(&bar[XB_XGEN(b.x)]) == gen, bar);
;             __builtin_amdgcn_fence(__ATOMIC_ACQUIRE, "agent");
;             asm volatile("s_waitcnt vmcnt(0)" ::: "memory");
;         }
.LBB0_787:
	s_waitcnt vmcnt(0) lgkmcnt(0)
	s_barrier
	v_cmp_eq_u32_e32 vcc, 0, v0
	s_and_saveexec_b64 s[0:1], vcc
	s_cbranch_execz .Lgb4_join
	v_mov_b32_e32 v1, s85
	ds_read_b32 v2, v1
	ds_read_b32 v3, v1 offset:4
	s_lshl_b32 s4, s84, 8
	s_add_u32 s4, s22, s4
	s_addc_u32 s5, s23, 0
	v_mov_b32_e32 v4, 0x1000
	v_mov_b32_e32 v5, 1
	global_atomic_add v5, v4, v5, s[4:5] offset:1024 sc0
	s_lshl_b32 s11, s84, 7
	s_addk_i32 s11, 0x3600
	s_waitcnt lgkmcnt(0)
	v_readfirstlane_b32 s6, v2
	v_readfirstlane_b32 s7, v3
	v_mov_b32_e32 v1, s11
	s_nop 3
	s_mul_i32 s14, s6, 5
	s_add_i32 s14, s14, -1
	s_mul_i32 s7, s7, 4
	s_waitcnt vmcnt(0)
	v_readfirstlane_b32 s15, v5
	v_mov_b32_e32 v4, 0x3600
	s_nop 3
	s_cmp_lg_u32 s15, s14
	s_cbranch_scc1 .Lgb4_poll
	buffer_wbl2 sc1
	s_waitcnt vmcnt(0)
	v_mov_b32_e32 v5, 1
	global_atomic_add v4, v5, s[22:23]
	global_atomic_add v4, v5, s[22:23] offset:128
	global_atomic_add v4, v5, s[22:23] offset:256
	global_atomic_add v4, v5, s[22:23] offset:384
	global_atomic_add v4, v5, s[22:23] offset:512
	global_atomic_add v4, v5, s[22:23] offset:640
	global_atomic_add v4, v5, s[22:23] offset:768
	global_atomic_add v4, v5, s[22:23] offset:896
	global_atomic_add v4, v5, s[22:23] offset:1024
	global_atomic_add v4, v5, s[22:23] offset:1152
	global_atomic_add v4, v5, s[22:23] offset:1280
	global_atomic_add v4, v5, s[22:23] offset:1408
	global_atomic_add v4, v5, s[22:23] offset:1536
	global_atomic_add v4, v5, s[22:23] offset:1664
	global_atomic_add v4, v5, s[22:23] offset:1792
	global_atomic_add v4, v5, s[22:23] offset:1920
